# v4: v3 rotated - next tile kk=0 fragment reads issued after the visibility barrier, before the last 8 MFMAs
# baseline (speedup 1.0000x reference)
.LBB0_104:
	v_mov_b32_e32 v1, v168
	v_readlane_b32 s52, v254, 48
	v_readfirstlane_b32 s2, v1
	s_lshl_b32 s3, s2, 5
	s_lshl_b32 s2, s2, 6
	v_lshrrev_b32_e32 v3, 4, v1
	v_and_b32_e32 v4, 7, v1
	s_and_b32 s3, s3, 0xfffff000
	v_lshlrev_b32_e32 v1, 6, v1
	s_and_b32 s2, s2, 0x1000
	v_readlane_b32 s56, v254, 52
	v_bitop3_b32 v3, v3, v4, 3 bitop3:0x6c
	v_and_b32_e32 v1, 0x3c0, v1
	v_readlane_b32 s57, v254, 53
	s_add_u32 s36, s56, s21
	v_lshlrev_b32_e32 v69, 3, v3
	s_waitcnt vmcnt(0)
	v_or_b32_e32 v3, s3, v1
	v_or_b32_e32 v4, s2, v1
	s_addc_u32 s37, s57, s20
	s_lshl_b64 s[2:3], s[30:31], 1
	s_add_u32 s40, s56, s2
	s_waitcnt lgkmcnt(0)
	v_mov_b32_e32 v32, 0
	v_xor_b32_e32 v1, 32, v69
	s_addc_u32 s41, s57, s3
	s_mov_b64 s[42:43], 0
	s_mov_b32 s51, 0
	v_lshlrev_b32_e32 v3, 1, v3
	v_lshlrev_b32_e32 v68, 1, v4
	v_mov_b32_e32 v33, v32
	v_mov_b32_e32 v34, v32
	v_mov_b32_e32 v35, v32
	v_mov_b32_e32 v48, v32
	v_mov_b32_e32 v49, v32
	v_mov_b32_e32 v50, v32
	v_mov_b32_e32 v51, v32
	v_mov_b32_e32 v4, v32
	v_mov_b32_e32 v5, v32
	v_mov_b32_e32 v6, v32
	v_mov_b32_e32 v7, v32
	v_mov_b32_e32 v8, v32
	v_mov_b32_e32 v9, v32
	v_mov_b32_e32 v10, v32
	v_mov_b32_e32 v11, v32
	v_mov_b32_e32 v12, v32
	v_mov_b32_e32 v13, v32
	v_mov_b32_e32 v14, v32
	v_mov_b32_e32 v15, v32
	v_mov_b32_e32 v16, v32
	v_mov_b32_e32 v17, v32
	v_mov_b32_e32 v18, v32
	v_mov_b32_e32 v19, v32
	v_mov_b32_e32 v20, v32
	v_mov_b32_e32 v21, v32
	v_mov_b32_e32 v22, v32
	v_mov_b32_e32 v23, v32
	v_mov_b32_e32 v24, v32
	v_mov_b32_e32 v25, v32
	v_mov_b32_e32 v26, v32
	v_mov_b32_e32 v27, v32
	v_mov_b32_e32 v28, v32
	v_mov_b32_e32 v29, v32
	v_mov_b32_e32 v30, v32
	v_mov_b32_e32 v31, v32
	v_mov_b32_e32 v36, v32
	v_mov_b32_e32 v37, v32
	v_mov_b32_e32 v38, v32
	v_mov_b32_e32 v39, v32
	v_mov_b32_e32 v40, v32
	v_mov_b32_e32 v41, v32
	v_mov_b32_e32 v42, v32
	v_mov_b32_e32 v43, v32
	v_mov_b32_e32 v44, v32
	v_mov_b32_e32 v45, v32
	v_mov_b32_e32 v46, v32
	v_mov_b32_e32 v47, v32
	v_mov_b32_e32 v52, v32
	v_mov_b32_e32 v53, v32
	v_mov_b32_e32 v54, v32
	v_mov_b32_e32 v55, v32
	v_mov_b32_e32 v56, v32
	v_mov_b32_e32 v57, v32
	v_mov_b32_e32 v58, v32
	v_mov_b32_e32 v59, v32
	v_mov_b32_e32 v60, v32
	v_mov_b32_e32 v61, v32
	v_mov_b32_e32 v62, v32
	v_mov_b32_e32 v63, v32
	v_mov_b32_e32 v64, v32
	v_mov_b32_e32 v65, v32
	v_mov_b32_e32 v66, v32
	v_mov_b32_e32 v67, v32
	s_mov_b64 s[18:19], 0x1390080
	s_waitcnt vmcnt(0) lgkmcnt(0)
	s_barrier
	v_readlane_b32 s53, v254, 49
	v_readlane_b32 s54, v254, 50
	v_readlane_b32 s55, v254, 51
	v_readlane_b32 s58, v254, 54
	v_readlane_b32 s59, v254, 55
	v_lshlrev_b32_e32 v86, 1, v69
	v_add_u32_e32 v160, v3, v86
	v_add_u32_e32 v162, v68, v86
	v_lshlrev_b32_e32 v86, 1, v1
	v_add_u32_e32 v161, v3, v86
	v_add_u32_e32 v163, v68, v86
	v_lshrrev_b32_e32 v87, 3, v168
	v_xor_b32_e32 v86, v87, v168
	v_and_b32_e32 v86, 7, v86
	v_lshlrev_b32_e32 v86, 4, v86
	s_movk_i32 s35, 0x1600
	v_mad_u32_u24 v164, v87, s35, v86
	v_add_u32_e32 v165, 0x2c000, v164
	v_add_u32_e32 v166, 0x58000, v164
	v_add_u32_e32 v167, 0x84000, v164
	s_add_u32 s52, s36, 0x1390080
	s_addc_u32 s53, s37, 0
	s_add_u32 s54, s40, 0xf4b0080
	s_addc_u32 s55, s41, 0
	v_readfirstlane_b32 s35, v168
	s_lshl_b32 s35, s35, 4
	s_or_b32 s35, s35, 0x8000
	s_mov_b32 m0, s35
	s_nop 0
	global_load_lds_dwordx4 v164, s[52:53]
	s_add_u32 m0, s35, 0x1000
	s_nop 0
	global_load_lds_dwordx4 v165, s[52:53]
	s_add_u32 m0, s35, 0x2000
	s_nop 0
	global_load_lds_dwordx4 v166, s[52:53]
	s_add_u32 m0, s35, 0x3000
	s_nop 0
	global_load_lds_dwordx4 v167, s[52:53]
	s_add_u32 m0, s35, 0x4000
	s_nop 0
	global_load_lds_dwordx4 v164, s[54:55]
	s_add_u32 m0, s35, 0x5000
	s_nop 0
	global_load_lds_dwordx4 v165, s[54:55]
	s_add_u32 m0, s35, 0x6000
	s_nop 0
	global_load_lds_dwordx4 v166, s[54:55]
	s_add_u32 m0, s35, 0x7000
	s_nop 0
	global_load_lds_dwordx4 v167, s[54:55]
	s_add_u32 s52, s52, 0x80
	s_addc_u32 s53, s53, 0
	s_add_u32 s54, s54, 0x80
	s_addc_u32 s55, s55, 0
	s_xor_b32 s35, s35, 0x8000
	ds_read_b128 v[70:73], v160
	ds_read_b128 v[74:77], v160 offset:2048
	ds_read_b128 v[78:81], v160 offset:4096
	ds_read_b128 v[82:85], v160 offset:6144
	ds_read_b128 v[112:115], v162 offset:16384
	ds_read_b128 v[116:119], v162 offset:18432
	ds_read_b128 v[120:123], v162 offset:20480
	ds_read_b128 v[124:127], v162 offset:22528
	v_xor_b32_e32 v160, 0x8000, v160
	v_xor_b32_e32 v162, 0x8000, v162
.LBB0_105:
	ds_read_b128 v[128:131], v161
	ds_read_b128 v[132:135], v161 offset:2048
	ds_read_b128 v[136:139], v161 offset:4096
	ds_read_b128 v[140:143], v161 offset:6144
	ds_read_b128 v[144:147], v163 offset:16384
	ds_read_b128 v[148:151], v163 offset:18432
	ds_read_b128 v[152:155], v163 offset:20480
	s_waitcnt lgkmcnt(10)
	v_mfma_f32_16x16x32_bf16 v[64:67], v[112:115], v[70:73], v[64:67]
	v_mfma_f32_16x16x32_bf16 v[60:63], v[112:115], v[74:77], v[60:63]
	v_mfma_f32_16x16x32_bf16 v[56:59], v[112:115], v[78:81], v[56:59]
	v_mfma_f32_16x16x32_bf16 v[52:55], v[112:115], v[82:85], v[52:55]
	ds_read_b128 v[156:159], v163 offset:22528
	v_xor_b32_e32 v161, 0x8000, v161
	v_xor_b32_e32 v163, 0x8000, v163
	s_waitcnt lgkmcnt(10)
	v_mfma_f32_16x16x32_bf16 v[44:47], v[116:119], v[70:73], v[44:47]
	v_mfma_f32_16x16x32_bf16 v[40:43], v[116:119], v[74:77], v[40:43]
	v_mfma_f32_16x16x32_bf16 v[36:39], v[116:119], v[78:81], v[36:39]
	v_mfma_f32_16x16x32_bf16 v[28:31], v[116:119], v[82:85], v[28:31]
	s_waitcnt lgkmcnt(9)
	v_mfma_f32_16x16x32_bf16 v[24:27], v[120:123], v[70:73], v[24:27]
	v_mfma_f32_16x16x32_bf16 v[20:23], v[120:123], v[74:77], v[20:23]
	v_mfma_f32_16x16x32_bf16 v[16:19], v[120:123], v[78:81], v[16:19]
	v_mfma_f32_16x16x32_bf16 v[12:15], v[120:123], v[82:85], v[12:15]
	s_waitcnt lgkmcnt(8)
	v_mfma_f32_16x16x32_bf16 v[8:11], v[124:127], v[70:73], v[8:11]
	v_mfma_f32_16x16x32_bf16 v[4:7], v[124:127], v[74:77], v[4:7]
	v_mfma_f32_16x16x32_bf16 v[48:51], v[124:127], v[78:81], v[48:51]
	v_mfma_f32_16x16x32_bf16 v[32:35], v[124:127], v[82:85], v[32:35]
	s_waitcnt lgkmcnt(0)
	s_barrier
	s_cmp_eq_u32 s42, 0x1500
	s_cbranch_scc1 .Lv4_nodma_G7
	s_mov_b32 m0, s35
	v_mfma_f32_16x16x32_bf16 v[64:67], v[144:147], v[128:131], v[64:67]
	global_load_lds_dwordx4 v164, s[52:53]
	s_add_u32 m0, s35, 0x1000
	v_mfma_f32_16x16x32_bf16 v[60:63], v[144:147], v[132:135], v[60:63]
	global_load_lds_dwordx4 v165, s[52:53]
	s_add_u32 m0, s35, 0x2000
	v_mfma_f32_16x16x32_bf16 v[56:59], v[144:147], v[136:139], v[56:59]
	global_load_lds_dwordx4 v166, s[52:53]
	s_add_u32 m0, s35, 0x3000
	v_mfma_f32_16x16x32_bf16 v[52:55], v[144:147], v[140:143], v[52:55]
	global_load_lds_dwordx4 v167, s[52:53]
	s_add_u32 m0, s35, 0x4000
	v_mfma_f32_16x16x32_bf16 v[44:47], v[148:151], v[128:131], v[44:47]
	global_load_lds_dwordx4 v164, s[54:55]
	s_add_u32 m0, s35, 0x5000
	v_mfma_f32_16x16x32_bf16 v[40:43], v[148:151], v[132:135], v[40:43]
	global_load_lds_dwordx4 v165, s[54:55]
	s_add_u32 m0, s35, 0x6000
	v_mfma_f32_16x16x32_bf16 v[36:39], v[148:151], v[136:139], v[36:39]
	global_load_lds_dwordx4 v166, s[54:55]
	s_add_u32 m0, s35, 0x7000
	v_mfma_f32_16x16x32_bf16 v[28:31], v[148:151], v[140:143], v[28:31]
	global_load_lds_dwordx4 v167, s[54:55]
	s_add_u32 s52, s52, 0x80
	s_addc_u32 s53, s53, 0
	s_add_u32 s54, s54, 0x80
	s_addc_u32 s55, s55, 0
	s_xor_b32 s35, s35, 0x8000
	s_waitcnt vmcnt(8)
	s_branch .Lv4_join_G7
.Lv4_nodma_G7:
	v_mfma_f32_16x16x32_bf16 v[64:67], v[144:147], v[128:131], v[64:67]
	v_mfma_f32_16x16x32_bf16 v[60:63], v[144:147], v[132:135], v[60:63]
	v_mfma_f32_16x16x32_bf16 v[56:59], v[144:147], v[136:139], v[56:59]
	v_mfma_f32_16x16x32_bf16 v[52:55], v[144:147], v[140:143], v[52:55]
	v_mfma_f32_16x16x32_bf16 v[44:47], v[148:151], v[128:131], v[44:47]
	v_mfma_f32_16x16x32_bf16 v[40:43], v[148:151], v[132:135], v[40:43]
	v_mfma_f32_16x16x32_bf16 v[36:39], v[148:151], v[136:139], v[36:39]
	v_mfma_f32_16x16x32_bf16 v[28:31], v[148:151], v[140:143], v[28:31]
	s_waitcnt vmcnt(0)
.Lv4_join_G7:
	s_barrier
	ds_read_b128 v[70:73], v160
	ds_read_b128 v[74:77], v160 offset:2048
	ds_read_b128 v[78:81], v160 offset:4096
	ds_read_b128 v[82:85], v160 offset:6144
	ds_read_b128 v[112:115], v162 offset:16384
	ds_read_b128 v[116:119], v162 offset:18432
	ds_read_b128 v[120:123], v162 offset:20480
	ds_read_b128 v[124:127], v162 offset:22528
	v_xor_b32_e32 v160, 0x8000, v160
	v_xor_b32_e32 v162, 0x8000, v162
	s_add_u32 s42, s42, 0x80
	s_cmpk_eq_i32 s42, 0x1580
	v_mfma_f32_16x16x32_bf16 v[24:27], v[152:155], v[128:131], v[24:27]
	v_mfma_f32_16x16x32_bf16 v[20:23], v[152:155], v[132:135], v[20:23]
	v_mfma_f32_16x16x32_bf16 v[16:19], v[152:155], v[136:139], v[16:19]
	v_mfma_f32_16x16x32_bf16 v[12:15], v[152:155], v[140:143], v[12:15]
	v_mfma_f32_16x16x32_bf16 v[8:11], v[156:159], v[128:131], v[8:11]
	v_mfma_f32_16x16x32_bf16 v[4:7], v[156:159], v[132:135], v[4:7]
	v_mfma_f32_16x16x32_bf16 v[48:51], v[156:159], v[136:139], v[48:51]
	v_mfma_f32_16x16x32_bf16 v[32:35], v[156:159], v[140:143], v[32:35]
	s_cbranch_scc0 .LBB0_105
	s_mov_b32 s49, 0x8000
	v_lshl_add_u32 v69, v69, 1, s49
	v_add_u32_e32 v90, v69, v68
	ds_read_b128 v[70:73], v90 offset:16384
	v_add_u32_e32 v69, v69, v3
	ds_read_b128 v[74:77], v69
	ds_read_b128 v[78:81], v69 offset:2048
	ds_read_b128 v[82:85], v69 offset:4096
	ds_read_b128 v[86:89], v69 offset:6144
	v_lshl_add_u32 v1, v1, 1, s49
	v_add_u32_e32 v98, v1, v68
	ds_read_b128 v[94:97], v98 offset:20480
	s_waitcnt lgkmcnt(4)
	v_mfma_f32_16x16x32_bf16 v[64:67], v[70:73], v[74:77], v[64:67]
	v_add_u32_e32 v1, v1, v3
	s_add_i32 s44, s44, 1
	v_readlane_b32 s1, v254, 22
	s_waitcnt lgkmcnt(3)
	v_mfma_f32_16x16x32_bf16 v[60:63], v[70:73], v[78:81], v[60:63]
	s_mul_i32 s2, s44, s1
	v_readlane_b32 s1, v253, 34
	s_add_i32 s2, s2, s1
	s_waitcnt lgkmcnt(2)
	v_mfma_f32_16x16x32_bf16 v[56:59], v[70:73], v[82:85], v[56:59]
	s_cmpk_gt_u32 s2, 0x5f
	s_cselect_b64 s[36:37], -1, 0
	s_lshr_b32 s42, s2, 3
	s_waitcnt lgkmcnt(1)
	v_mfma_f32_16x16x32_bf16 v[52:55], v[70:73], v[86:89], v[52:55]
	ds_read_b128 v[70:73], v90 offset:18432
	v_readlane_b32 s1, v253, 62
	s_min_u32 s3, s2, 0x60
	s_waitcnt lgkmcnt(0)
	v_mfma_f32_16x16x32_bf16 v[44:47], v[70:73], v[74:77], v[44:47]
	s_add_i32 s42, s42, s1
	s_and_b32 s43, s3, 7
	s_cmpk_lt_u32 s2, 0x60
	v_mfma_f32_16x16x32_bf16 v[40:43], v[70:73], v[78:81], v[40:43]
	v_mfma_f32_16x16x32_bf16 v[36:39], v[70:73], v[82:85], v[36:39]
	v_mfma_f32_16x16x32_bf16 v[28:31], v[70:73], v[86:89], v[28:31]
	ds_read_b128 v[70:73], v90 offset:20480
	s_waitcnt lgkmcnt(0)
	v_mfma_f32_16x16x32_bf16 v[24:27], v[70:73], v[74:77], v[24:27]
	v_mfma_f32_16x16x32_bf16 v[20:23], v[70:73], v[78:81], v[20:23]
	v_mfma_f32_16x16x32_bf16 v[16:19], v[70:73], v[82:85], v[16:19]
	v_mfma_f32_16x16x32_bf16 v[12:15], v[70:73], v[86:89], v[12:15]
	ds_read_b128 v[70:73], v90 offset:22528
	ds_read_b128 v[90:93], v1 offset:6144
	s_waitcnt lgkmcnt(1)
	v_mfma_f32_16x16x32_bf16 v[8:11], v[70:73], v[74:77], v[8:11]
	v_mfma_f32_16x16x32_bf16 v[4:7], v[70:73], v[78:81], v[4:7]
	ds_read_b128 v[78:81], v1
	v_mfma_f32_16x16x32_bf16 v[74:77], v[70:73], v[82:85], v[48:51]
	ds_read_b128 v[82:85], v1 offset:2048
	s_nop 1
	ds_read_b128 v[48:51], v98 offset:16384
	v_mfma_f32_16x16x32_bf16 v[68:71], v[70:73], v[86:89], v[32:35]
	ds_read_b128 v[86:89], v1 offset:4096
	s_nop 1
	ds_read_b128 v[32:35], v98 offset:18432
	ds_read_b128 v[98:101], v98 offset:22528
	s_waitcnt lgkmcnt(3)
	v_mfma_f32_16x16x32_bf16 v[64:67], v[48:51], v[78:81], v[64:67]
	s_waitcnt vmcnt(0)
	s_waitcnt lgkmcnt(0)
	s_barrier
	v_mfma_f32_16x16x32_bf16 v[60:63], v[48:51], v[82:85], v[60:63]
	v_mfma_f32_16x16x32_bf16 v[56:59], v[48:51], v[86:89], v[56:59]
	v_mfma_f32_16x16x32_bf16 v[52:55], v[48:51], v[90:93], v[52:55]
	v_mfma_f32_16x16x32_bf16 v[48:51], v[32:35], v[78:81], v[44:47]
	v_mfma_f32_16x16x32_bf16 v[44:47], v[32:35], v[82:85], v[40:43]
	v_mfma_f32_16x16x32_bf16 v[40:43], v[32:35], v[86:89], v[36:39]
	v_mfma_f32_16x16x32_bf16 v[36:39], v[32:35], v[90:93], v[28:31]
	v_mfma_f32_16x16x32_bf16 v[32:35], v[94:97], v[78:81], v[24:27]
	v_mfma_f32_16x16x32_bf16 v[28:31], v[94:97], v[82:85], v[20:23]
	v_mfma_f32_16x16x32_bf16 v[24:27], v[94:97], v[86:89], v[16:19]
	v_mfma_f32_16x16x32_bf16 v[20:23], v[94:97], v[90:93], v[12:15]
	v_mfma_f32_16x16x32_bf16 v[16:19], v[98:101], v[78:81], v[8:11]
	v_mfma_f32_16x16x32_bf16 v[12:15], v[98:101], v[82:85], v[4:7]
	v_mfma_f32_16x16x32_bf16 v[8:11], v[98:101], v[86:89], v[74:77]
	v_mfma_f32_16x16x32_bf16 v[4:7], v[98:101], v[90:93], v[68:71]
	s_cbranch_scc0 .LBB0_99
	s_mul_i32 s30, s42, 0x58000
	s_lshl_b64 s[2:3], s[30:31], 1
	v_readlane_b32 s18, v252, 26
	v_readlane_b32 s19, v252, 27
	s_add_u32 s2, s18, s2
	s_addc_u32 s3, s19, s3
	s_mul_i32 s20, s43, 0xb0000
	v_readlane_b32 s1, v252, 28
	s_add_u32 s20, s1, s20
	v_readlane_b32 s1, v252, 29
	v_mov_b32_e32 v1, v168
	s_addc_u32 s21, s1, 0
	v_mov_b64_e32 v[68:69], s[2:3]
	v_ashrrev_i32_e32 v3, 3, v1
	v_xor_b32_e32 v70, v3, v1
	v_mov_b64_e32 v[72:73], s[20:21]
	v_mad_i64_i32 v[68:69], s[2:3], v3, s34, v[68:69]
	v_lshlrev_b32_e32 v70, 4, v70
	v_mad_i64_i32 v[72:73], s[2:3], v3, s34, v[72:73]
	v_lshlrev_b32_e32 v1, 4, v1
	v_and_b32_e32 v70, 0x70, v70
	v_mov_b32_e32 v71, v2
	v_readfirstlane_b32 s2, v1
	v_add_u32_e32 v3, 0x1000, v1
	v_lshl_add_u64 v[68:69], v[68:69], 0, v[70:71]
	s_mov_b32 m0, s2
	s_mov_b64 s[18:19], 0x2c000
	v_readfirstlane_b32 s2, v3
	v_add_u32_e32 v3, 0x2000, v1
	global_load_lds_dwordx4 v[68:69], off
	v_lshl_add_u64 v[74:75], v[68:69], 0, s[18:19]
	s_mov_b32 m0, s2
	s_mov_b64 s[20:21], 0x58000
	v_readfirstlane_b32 s2, v3
	v_add_u32_e32 v3, 0x3000, v1
	global_load_lds_dwordx4 v[74:75], off
	v_lshl_add_u64 v[74:75], v[68:69], 0, s[20:21]
	s_mov_b32 m0, s2
	s_mov_b64 s[34:35], 0x84000
	v_readfirstlane_b32 s2, v3
	v_add_u32_e32 v3, 0x4000, v1
	global_load_lds_dwordx4 v[74:75], off
	v_lshl_add_u64 v[68:69], v[68:69], 0, s[34:35]
	s_mov_b32 m0, s2
	v_readfirstlane_b32 s2, v3
	v_add_u32_e32 v3, 0x5000, v1
	global_load_lds_dwordx4 v[68:69], off
	v_lshl_add_u64 v[68:69], v[72:73], 0, v[70:71]
	s_mov_b32 m0, s2
	v_readfirstlane_b32 s2, v3
	v_add_u32_e32 v3, 0x6000, v1
	global_load_lds_dwordx4 v[68:69], off
	v_lshl_add_u64 v[70:71], v[68:69], 0, s[18:19]
	s_mov_b32 m0, s2
	v_readfirstlane_b32 s2, v3
	v_add_u32_e32 v1, 0x7000, v1
	global_load_lds_dwordx4 v[70:71], off
	v_lshl_add_u64 v[70:71], v[68:69], 0, s[20:21]
	s_mov_b32 m0, s2
	v_readfirstlane_b32 s2, v1
	global_load_lds_dwordx4 v[70:71], off
	v_lshl_add_u64 v[68:69], v[68:69], 0, s[34:35]
	s_mov_b32 m0, s2
	s_nop 0
	global_load_lds_dwordx4 v[68:69], off
	s_branch .LBB0_99

.LBB0_121:
	v_mov_b32_e32 v1, v168
	v_readlane_b32 s60, v254, 48
	v_readfirstlane_b32 s2, v1
	s_lshl_b32 s3, s2, 5
	s_lshl_b32 s2, s2, 6
	s_and_b32 s3, s3, 0xfffff000
	s_and_b32 s2, s2, 0x1000
	v_readlane_b32 s64, v254, 52
	v_lshrrev_b32_e32 v3, 4, v1
	v_and_b32_e32 v4, 7, v1
	v_lshlrev_b32_e32 v1, 6, v1
	v_readlane_b32 s65, v254, 53
	s_add_u32 s50, s64, s50
	v_bitop3_b32 v3, v3, v4, 3 bitop3:0x6c
	s_waitcnt vmcnt(0)
	v_and_b32_e32 v1, 0x3c0, v1
	s_addc_u32 s51, s65, s51
	v_lshlrev_b32_e32 v69, 3, v3
	v_or_b32_e32 v3, s3, v1
	v_or_b32_e32 v4, s2, v1
	s_add_u32 s52, s64, s52
	s_waitcnt lgkmcnt(0)
	v_mov_b32_e32 v32, 0
	v_xor_b32_e32 v1, 32, v69
	s_addc_u32 s53, s65, s53
	s_mov_b64 s[54:55], 0
	s_mov_b32 s45, 0
	v_lshlrev_b32_e32 v3, 1, v3
	v_lshlrev_b32_e32 v68, 1, v4
	v_mov_b32_e32 v33, v32
	v_mov_b32_e32 v34, v32
	v_mov_b32_e32 v35, v32
	v_mov_b32_e32 v48, v32
	v_mov_b32_e32 v49, v32
	v_mov_b32_e32 v50, v32
	v_mov_b32_e32 v51, v32
	v_mov_b32_e32 v4, v32
	v_mov_b32_e32 v5, v32
	v_mov_b32_e32 v6, v32
	v_mov_b32_e32 v7, v32
	v_mov_b32_e32 v8, v32
	v_mov_b32_e32 v9, v32
	v_mov_b32_e32 v10, v32
	v_mov_b32_e32 v11, v32
	v_mov_b32_e32 v12, v32
	v_mov_b32_e32 v13, v32
	v_mov_b32_e32 v14, v32
	v_mov_b32_e32 v15, v32
	v_mov_b32_e32 v16, v32
	v_mov_b32_e32 v17, v32
	v_mov_b32_e32 v18, v32
	v_mov_b32_e32 v19, v32
	v_mov_b32_e32 v20, v32
	v_mov_b32_e32 v21, v32
	v_mov_b32_e32 v22, v32
	v_mov_b32_e32 v23, v32
	v_mov_b32_e32 v24, v32
	v_mov_b32_e32 v25, v32
	v_mov_b32_e32 v26, v32
	v_mov_b32_e32 v27, v32
	v_mov_b32_e32 v28, v32
	v_mov_b32_e32 v29, v32
	v_mov_b32_e32 v30, v32
	v_mov_b32_e32 v31, v32
	v_mov_b32_e32 v36, v32
	v_mov_b32_e32 v37, v32
	v_mov_b32_e32 v38, v32
	v_mov_b32_e32 v39, v32
	v_mov_b32_e32 v40, v32
	v_mov_b32_e32 v41, v32
	v_mov_b32_e32 v42, v32
	v_mov_b32_e32 v43, v32
	v_mov_b32_e32 v44, v32
	v_mov_b32_e32 v45, v32
	v_mov_b32_e32 v46, v32
	v_mov_b32_e32 v47, v32
	v_mov_b32_e32 v52, v32
	v_mov_b32_e32 v53, v32
	v_mov_b32_e32 v54, v32
	v_mov_b32_e32 v55, v32
	v_mov_b32_e32 v56, v32
	v_mov_b32_e32 v57, v32
	v_mov_b32_e32 v58, v32
	v_mov_b32_e32 v59, v32
	v_mov_b32_e32 v60, v32
	v_mov_b32_e32 v61, v32
	v_mov_b32_e32 v62, v32
	v_mov_b32_e32 v63, v32
	v_mov_b32_e32 v64, v32
	v_mov_b32_e32 v65, v32
	v_mov_b32_e32 v66, v32
	v_mov_b32_e32 v67, v32
	s_waitcnt vmcnt(0) lgkmcnt(0)
	s_barrier
	v_readlane_b32 s61, v254, 49
	v_readlane_b32 s62, v254, 50
	v_readlane_b32 s63, v254, 51
	v_readlane_b32 s66, v254, 54
	v_readlane_b32 s67, v254, 55
	v_lshlrev_b32_e32 v86, 1, v69
	v_add_u32_e32 v160, v3, v86
	v_add_u32_e32 v162, v68, v86
	v_lshlrev_b32_e32 v86, 1, v1
	v_add_u32_e32 v161, v3, v86
	v_add_u32_e32 v163, v68, v86
	v_lshrrev_b32_e32 v87, 3, v168
	v_xor_b32_e32 v86, v87, v168
	v_and_b32_e32 v86, 7, v86
	v_lshlrev_b32_e32 v86, 4, v86
	s_movk_i32 s60, 0x800
	v_mad_u32_u24 v164, v87, s60, v86
	v_add_u32_e32 v165, 0x10000, v164
	v_add_u32_e32 v166, 0x20000, v164
	v_add_u32_e32 v167, 0x30000, v164
	s_add_u32 s58, s50, s68
	s_addc_u32 s59, s51, s69
	s_add_u32 s34, s52, 0xa130080
	s_addc_u32 s35, s53, 0
	v_readfirstlane_b32 s60, v168
	s_lshl_b32 s60, s60, 4
	s_or_b32 s60, s60, 0x8000
	s_mov_b32 m0, s60
	s_nop 0
	global_load_lds_dwordx4 v164, s[58:59]
	s_add_u32 m0, s60, 0x1000
	s_nop 0
	global_load_lds_dwordx4 v165, s[58:59]
	s_add_u32 m0, s60, 0x2000
	s_nop 0
	global_load_lds_dwordx4 v166, s[58:59]
	s_add_u32 m0, s60, 0x3000
	s_nop 0
	global_load_lds_dwordx4 v167, s[58:59]
	s_add_u32 m0, s60, 0x4000
	s_nop 0
	global_load_lds_dwordx4 v164, s[34:35]
	s_add_u32 m0, s60, 0x5000
	s_nop 0
	global_load_lds_dwordx4 v165, s[34:35]
	s_add_u32 m0, s60, 0x6000
	s_nop 0
	global_load_lds_dwordx4 v166, s[34:35]
	s_add_u32 m0, s60, 0x7000
	s_nop 0
	global_load_lds_dwordx4 v167, s[34:35]
	s_add_u32 s58, s58, 0x80
	s_addc_u32 s59, s59, 0
	s_add_u32 s34, s34, 0x80
	s_addc_u32 s35, s35, 0
	s_xor_b32 s60, s60, 0x8000
	ds_read_b128 v[70:73], v160
	ds_read_b128 v[74:77], v160 offset:2048
	ds_read_b128 v[78:81], v160 offset:4096
	ds_read_b128 v[82:85], v160 offset:6144
	ds_read_b128 v[112:115], v162 offset:16384
	ds_read_b128 v[116:119], v162 offset:18432
	ds_read_b128 v[120:123], v162 offset:20480
	ds_read_b128 v[124:127], v162 offset:22528
	v_xor_b32_e32 v160, 0x8000, v160
	v_xor_b32_e32 v162, 0x8000, v162
.LBB0_122:
	ds_read_b128 v[128:131], v161
	ds_read_b128 v[132:135], v161 offset:2048
	ds_read_b128 v[136:139], v161 offset:4096
	ds_read_b128 v[140:143], v161 offset:6144
	ds_read_b128 v[144:147], v163 offset:16384
	ds_read_b128 v[148:151], v163 offset:18432
	ds_read_b128 v[152:155], v163 offset:20480
	s_waitcnt lgkmcnt(10)
	v_mfma_f32_16x16x32_bf16 v[64:67], v[112:115], v[70:73], v[64:67]
	v_mfma_f32_16x16x32_bf16 v[60:63], v[112:115], v[74:77], v[60:63]
	v_mfma_f32_16x16x32_bf16 v[56:59], v[112:115], v[78:81], v[56:59]
	v_mfma_f32_16x16x32_bf16 v[52:55], v[112:115], v[82:85], v[52:55]
	ds_read_b128 v[156:159], v163 offset:22528
	v_xor_b32_e32 v161, 0x8000, v161
	v_xor_b32_e32 v163, 0x8000, v163
	s_waitcnt lgkmcnt(10)
	v_mfma_f32_16x16x32_bf16 v[44:47], v[116:119], v[70:73], v[44:47]
	v_mfma_f32_16x16x32_bf16 v[40:43], v[116:119], v[74:77], v[40:43]
	v_mfma_f32_16x16x32_bf16 v[36:39], v[116:119], v[78:81], v[36:39]
	v_mfma_f32_16x16x32_bf16 v[28:31], v[116:119], v[82:85], v[28:31]
	s_waitcnt lgkmcnt(9)
	v_mfma_f32_16x16x32_bf16 v[24:27], v[120:123], v[70:73], v[24:27]
	v_mfma_f32_16x16x32_bf16 v[20:23], v[120:123], v[74:77], v[20:23]
	v_mfma_f32_16x16x32_bf16 v[16:19], v[120:123], v[78:81], v[16:19]
	v_mfma_f32_16x16x32_bf16 v[12:15], v[120:123], v[82:85], v[12:15]
	s_waitcnt lgkmcnt(8)
	v_mfma_f32_16x16x32_bf16 v[8:11], v[124:127], v[70:73], v[8:11]
	v_mfma_f32_16x16x32_bf16 v[4:7], v[124:127], v[74:77], v[4:7]
	v_mfma_f32_16x16x32_bf16 v[48:51], v[124:127], v[78:81], v[48:51]
	v_mfma_f32_16x16x32_bf16 v[32:35], v[124:127], v[82:85], v[32:35]
	s_waitcnt lgkmcnt(0)
	s_barrier
	s_cmp_eq_u32 s54, 0x700
	s_cbranch_scc1 .Lv4_nodma_G6
	s_mov_b32 m0, s60
	v_mfma_f32_16x16x32_bf16 v[64:67], v[144:147], v[128:131], v[64:67]
	global_load_lds_dwordx4 v164, s[58:59]
	s_add_u32 m0, s60, 0x1000
	v_mfma_f32_16x16x32_bf16 v[60:63], v[144:147], v[132:135], v[60:63]
	global_load_lds_dwordx4 v165, s[58:59]
	s_add_u32 m0, s60, 0x2000
	v_mfma_f32_16x16x32_bf16 v[56:59], v[144:147], v[136:139], v[56:59]
	global_load_lds_dwordx4 v166, s[58:59]
	s_add_u32 m0, s60, 0x3000
	v_mfma_f32_16x16x32_bf16 v[52:55], v[144:147], v[140:143], v[52:55]
	global_load_lds_dwordx4 v167, s[58:59]
	s_add_u32 m0, s60, 0x4000
	v_mfma_f32_16x16x32_bf16 v[44:47], v[148:151], v[128:131], v[44:47]
	global_load_lds_dwordx4 v164, s[34:35]
	s_add_u32 m0, s60, 0x5000
	v_mfma_f32_16x16x32_bf16 v[40:43], v[148:151], v[132:135], v[40:43]
	global_load_lds_dwordx4 v165, s[34:35]
	s_add_u32 m0, s60, 0x6000
	v_mfma_f32_16x16x32_bf16 v[36:39], v[148:151], v[136:139], v[36:39]
	global_load_lds_dwordx4 v166, s[34:35]
	s_add_u32 m0, s60, 0x7000
	v_mfma_f32_16x16x32_bf16 v[28:31], v[148:151], v[140:143], v[28:31]
	global_load_lds_dwordx4 v167, s[34:35]
	s_add_u32 s58, s58, 0x80
	s_addc_u32 s59, s59, 0
	s_add_u32 s34, s34, 0x80
	s_addc_u32 s35, s35, 0
	s_xor_b32 s60, s60, 0x8000
	s_waitcnt vmcnt(8)
	s_branch .Lv4_join_G6

.Lv4_join_G6:
	s_barrier
	ds_read_b128 v[70:73], v160
	ds_read_b128 v[74:77], v160 offset:2048
	ds_read_b128 v[78:81], v160 offset:4096
	ds_read_b128 v[82:85], v160 offset:6144
	ds_read_b128 v[112:115], v162 offset:16384
	ds_read_b128 v[116:119], v162 offset:18432
	ds_read_b128 v[120:123], v162 offset:20480
	ds_read_b128 v[124:127], v162 offset:22528
	v_xor_b32_e32 v160, 0x8000, v160
	v_xor_b32_e32 v162, 0x8000, v162
	s_add_u32 s54, s54, 0x80
	s_cmpk_eq_i32 s54, 0x780
	v_mfma_f32_16x16x32_bf16 v[24:27], v[152:155], v[128:131], v[24:27]
	v_mfma_f32_16x16x32_bf16 v[20:23], v[152:155], v[132:135], v[20:23]
	v_mfma_f32_16x16x32_bf16 v[16:19], v[152:155], v[136:139], v[16:19]
	v_mfma_f32_16x16x32_bf16 v[12:15], v[152:155], v[140:143], v[12:15]
	v_mfma_f32_16x16x32_bf16 v[8:11], v[156:159], v[128:131], v[8:11]
	v_mfma_f32_16x16x32_bf16 v[4:7], v[156:159], v[132:135], v[4:7]
	v_mfma_f32_16x16x32_bf16 v[48:51], v[156:159], v[136:139], v[48:51]
	v_mfma_f32_16x16x32_bf16 v[32:35], v[156:159], v[140:143], v[32:35]
	s_cbranch_scc0 .LBB0_122
	s_mov_b32 s37, 0x8000
	v_lshl_add_u32 v69, v69, 1, s37
	v_add_u32_e32 v102, v69, v68
	ds_read_b128 v[70:73], v102 offset:16384
	v_add_u32_e32 v69, v69, v3
	ds_read_b128 v[74:77], v69
	ds_read_b128 v[78:81], v69 offset:2048
	v_lshl_add_u32 v1, v1, 1, s37
	v_add_u32_e32 v68, v1, v68
	v_add_u32_e32 v1, v1, v3
	s_and_b64 vcc, exec, s[48:49]
	s_waitcnt lgkmcnt(0)
	v_mfma_f32_16x16x32_bf16 v[82:85], v[70:73], v[78:81], v[60:63]
	ds_read_b128 v[86:89], v69 offset:6144
	ds_read_b128 v[106:109], v1 offset:6144
	s_nop 0
	ds_read_b128 v[60:63], v69 offset:4096
	v_mfma_f32_16x16x32_bf16 v[64:67], v[70:73], v[74:77], v[64:67]
	s_waitcnt lgkmcnt(0)
	v_mfma_f32_16x16x32_bf16 v[56:59], v[70:73], v[60:63], v[56:59]
	v_mfma_f32_16x16x32_bf16 v[70:73], v[70:73], v[86:89], v[52:55]
	s_nop 2
	ds_read_b128 v[52:55], v102 offset:18432
	s_waitcnt lgkmcnt(0)
	v_mfma_f32_16x16x32_bf16 v[94:97], v[52:55], v[60:63], v[36:39]
	s_nop 2
	ds_read_b128 v[36:39], v102 offset:20480
	s_waitcnt lgkmcnt(0)
	v_mfma_f32_16x16x32_bf16 v[98:101], v[36:39], v[86:89], v[12:15]
	s_nop 2
	ds_read_b128 v[12:15], v102 offset:22528
	ds_read_b128 v[102:105], v1 offset:2048
	v_mfma_f32_16x16x32_bf16 v[90:93], v[52:55], v[74:77], v[44:47]
	v_mfma_f32_16x16x32_bf16 v[24:27], v[36:39], v[74:77], v[24:27]
	s_waitcnt lgkmcnt(1)
	v_mfma_f32_16x16x32_bf16 v[8:11], v[12:15], v[74:77], v[8:11]
	v_mfma_f32_16x16x32_bf16 v[74:77], v[12:15], v[78:81], v[4:7]
	s_nop 2
	ds_read_b128 v[4:7], v68 offset:16384
	v_mfma_f32_16x16x32_bf16 v[28:31], v[52:55], v[86:89], v[28:31]
	v_mfma_f32_16x16x32_bf16 v[86:89], v[12:15], v[86:89], v[32:35]
	s_nop 2
	ds_read_b128 v[32:35], v1
	v_mfma_f32_16x16x32_bf16 v[40:43], v[52:55], v[78:81], v[40:43]
	s_waitcnt lgkmcnt(1)
	v_mfma_f32_16x16x32_bf16 v[52:55], v[4:7], v[102:105], v[82:85]
	s_nop 2
	ds_read_b128 v[82:85], v1 offset:4096
	v_mfma_f32_16x16x32_bf16 v[20:23], v[36:39], v[78:81], v[20:23]
	v_mfma_f32_16x16x32_bf16 v[16:19], v[36:39], v[60:63], v[16:19]
	v_mfma_f32_16x16x32_bf16 v[78:81], v[12:15], v[60:63], v[48:51]
	s_waitcnt lgkmcnt(1)
	v_mfma_f32_16x16x32_bf16 v[60:63], v[4:7], v[32:35], v[64:67]
	s_waitcnt lgkmcnt(0)
	v_mfma_f32_16x16x32_bf16 v[44:47], v[4:7], v[82:85], v[56:59]
	v_mfma_f32_16x16x32_bf16 v[36:39], v[4:7], v[106:109], v[70:73]
	ds_read_b128 v[4:7], v68 offset:18432
	s_waitcnt lgkmcnt(0)
	v_mfma_f32_16x16x32_bf16 v[64:67], v[4:7], v[32:35], v[90:93]
	v_mfma_f32_16x16x32_bf16 v[56:59], v[4:7], v[102:105], v[40:43]
	v_mfma_f32_16x16x32_bf16 v[48:51], v[4:7], v[82:85], v[94:97]
	v_mfma_f32_16x16x32_bf16 v[40:43], v[4:7], v[106:109], v[28:31]
	ds_read_b128 v[4:7], v68 offset:20480
	ds_read_b128 v[68:71], v68 offset:22528
	s_waitcnt vmcnt(0)
	s_waitcnt lgkmcnt(1)
	v_mfma_f32_16x16x32_bf16 v[28:31], v[4:7], v[32:35], v[24:27]
	s_waitcnt lgkmcnt(0)
	s_barrier
	v_mfma_f32_16x16x32_bf16 v[20:23], v[4:7], v[102:105], v[20:23]
	v_mfma_f32_16x16x32_bf16 v[12:15], v[4:7], v[82:85], v[16:19]
	v_mfma_f32_16x16x32_bf16 v[4:7], v[4:7], v[106:109], v[98:101]
	v_mfma_f32_16x16x32_bf16 v[32:35], v[68:71], v[32:35], v[8:11]
	v_mfma_f32_16x16x32_bf16 v[24:27], v[68:71], v[102:105], v[74:77]
	v_mfma_f32_16x16x32_bf16 v[16:19], v[68:71], v[82:85], v[78:81]
	v_mfma_f32_16x16x32_bf16 v[8:11], v[68:71], v[106:109], v[86:89]
	s_cbranch_vccz .LBB0_125
	s_ashr_i32 s45, s44, 31
	v_mov_b32_e32 v1, v168
	s_lshl_b64 s[2:3], s[44:45], 18
	v_readlane_b32 s18, v252, 32
	v_readlane_b32 s19, v252, 33
	v_ashrrev_i32_e32 v68, 3, v1
	s_add_u32 s2, s18, s2
	v_xor_b32_e32 v3, v68, v1
	v_ashrrev_i32_e32 v69, 31, v68
	s_addc_u32 s3, s19, s3
	v_lshlrev_b64 v[68:69], 11, v[68:69]
	v_lshlrev_b32_e32 v3, 4, v3
	v_lshlrev_b32_e32 v1, 4, v1
	s_ashr_i32 s37, s36, 31
	v_lshl_add_u64 v[70:71], s[2:3], 0, v[68:69]
	v_and_b32_e32 v72, 0x70, v3
	v_mov_b32_e32 v73, v2
	v_readfirstlane_b32 s2, v1
	v_add_u32_e32 v3, 0x1000, v1
	s_lshl_b64 s[20:21], s[36:37], 18
	v_readlane_b32 s1, v252, 34
	v_lshl_add_u64 v[70:71], v[70:71], 0, v[72:73]
	s_mov_b32 m0, s2
	v_readfirstlane_b32 s2, v3
	v_add_u32_e32 v3, 0x2000, v1
	s_add_u32 s20, s1, s20
	v_readlane_b32 s1, v252, 35
	global_load_lds_dwordx4 v[70:71], off
	v_lshl_add_u64 v[74:75], v[70:71], 0, s[24:25]
	s_mov_b32 m0, s2
	v_readfirstlane_b32 s2, v3
	v_add_u32_e32 v3, 0x3000, v1
	s_addc_u32 s21, s1, s21
	global_load_lds_dwordx4 v[74:75], off
	v_lshl_add_u64 v[74:75], v[70:71], 0, s[26:27]
	s_mov_b32 m0, s2
	v_readfirstlane_b32 s2, v3
	v_add_u32_e32 v3, 0x4000, v1
	v_lshl_add_u64 v[68:69], s[20:21], 0, v[68:69]
	global_load_lds_dwordx4 v[74:75], off
	v_lshl_add_u64 v[70:71], v[70:71], 0, s[28:29]
	s_mov_b32 m0, s2
	v_readfirstlane_b32 s2, v3
	v_add_u32_e32 v3, 0x5000, v1
	global_load_lds_dwordx4 v[70:71], off
	v_lshl_add_u64 v[68:69], v[68:69], 0, v[72:73]
	s_mov_b32 m0, s2
	v_readfirstlane_b32 s2, v3
	v_add_u32_e32 v3, 0x6000, v1
	global_load_lds_dwordx4 v[68:69], off
	v_lshl_add_u64 v[70:71], v[68:69], 0, s[24:25]
	s_mov_b32 m0, s2
	v_readfirstlane_b32 s2, v3
	v_add_u32_e32 v1, 0x7000, v1
	global_load_lds_dwordx4 v[70:71], off
	v_lshl_add_u64 v[70:71], v[68:69], 0, s[26:27]
	s_mov_b32 m0, s2
	v_readfirstlane_b32 s2, v1
	global_load_lds_dwordx4 v[70:71], off
	v_lshl_add_u64 v[68:69], v[68:69], 0, s[28:29]
	s_mov_b32 m0, s2
	s_nop 0
	global_load_lds_dwordx4 v[68:69], off

.LBB0_148:
	v_mov_b32_e32 v1, v168
	v_readlane_b32 s52, v254, 48
	v_readfirstlane_b32 s2, v1
	v_lshrrev_b32_e32 v3, 4, v1
	v_and_b32_e32 v4, 7, v1
	s_lshl_b32 s3, s2, 5
	v_lshlrev_b32_e32 v1, 6, v1
	s_lshl_b32 s2, s2, 6
	v_bitop3_b32 v3, v3, v4, 3 bitop3:0x6c
	s_and_b32 s3, s3, 0xfffff000
	v_and_b32_e32 v1, 0x3c0, v1
	s_and_b32 s2, s2, 0x1000
	v_lshlrev_b32_e32 v69, 3, v3
	v_or_b32_e32 v3, s3, v1
	v_or_b32_e32 v4, s2, v1
	s_lshl_b64 s[2:3], s[38:39], 11
	v_readlane_b32 s56, v254, 52
	v_readlane_b32 s57, v254, 53
	s_add_u32 s40, s56, s2
	s_waitcnt vmcnt(0)
	s_addc_u32 s41, s57, s3
	s_lshl_b64 s[2:3], s[30:31], 1
	s_add_u32 s42, s56, s2
	s_waitcnt lgkmcnt(0)
	v_mov_b32_e32 v32, 0
	v_xor_b32_e32 v1, 32, v69
	s_addc_u32 s43, s57, s3
	s_mov_b64 s[44:45], 0
	s_mov_b32 s51, 0
	v_lshlrev_b32_e32 v3, 1, v3
	v_lshlrev_b32_e32 v68, 1, v4
	v_mov_b32_e32 v33, v32
	v_mov_b32_e32 v34, v32
	v_mov_b32_e32 v35, v32
	v_mov_b32_e32 v48, v32
	v_mov_b32_e32 v49, v32
	v_mov_b32_e32 v50, v32
	v_mov_b32_e32 v51, v32
	v_mov_b32_e32 v4, v32
	v_mov_b32_e32 v5, v32
	v_mov_b32_e32 v6, v32
	v_mov_b32_e32 v7, v32
	v_mov_b32_e32 v8, v32
	v_mov_b32_e32 v9, v32
	v_mov_b32_e32 v10, v32
	v_mov_b32_e32 v11, v32
	v_mov_b32_e32 v12, v32
	v_mov_b32_e32 v13, v32
	v_mov_b32_e32 v14, v32
	v_mov_b32_e32 v15, v32
	v_mov_b32_e32 v16, v32
	v_mov_b32_e32 v17, v32
	v_mov_b32_e32 v18, v32
	v_mov_b32_e32 v19, v32
	v_mov_b32_e32 v20, v32
	v_mov_b32_e32 v21, v32
	v_mov_b32_e32 v22, v32
	v_mov_b32_e32 v23, v32
	v_mov_b32_e32 v24, v32
	v_mov_b32_e32 v25, v32
	v_mov_b32_e32 v26, v32
	v_mov_b32_e32 v27, v32
	v_mov_b32_e32 v28, v32
	v_mov_b32_e32 v29, v32
	v_mov_b32_e32 v30, v32
	v_mov_b32_e32 v31, v32
	v_mov_b32_e32 v36, v32
	v_mov_b32_e32 v37, v32
	v_mov_b32_e32 v38, v32
	v_mov_b32_e32 v39, v32
	v_mov_b32_e32 v40, v32
	v_mov_b32_e32 v41, v32
	v_mov_b32_e32 v42, v32
	v_mov_b32_e32 v43, v32
	v_mov_b32_e32 v44, v32
	v_mov_b32_e32 v45, v32
	v_mov_b32_e32 v46, v32
	v_mov_b32_e32 v47, v32
	v_mov_b32_e32 v52, v32
	v_mov_b32_e32 v53, v32
	v_mov_b32_e32 v54, v32
	v_mov_b32_e32 v55, v32
	v_mov_b32_e32 v56, v32
	v_mov_b32_e32 v57, v32
	v_mov_b32_e32 v58, v32
	v_mov_b32_e32 v59, v32
	v_mov_b32_e32 v60, v32
	v_mov_b32_e32 v61, v32
	v_mov_b32_e32 v62, v32
	v_mov_b32_e32 v63, v32
	v_mov_b32_e32 v64, v32
	v_mov_b32_e32 v65, v32
	v_mov_b32_e32 v66, v32
	v_mov_b32_e32 v67, v32
	s_mov_b64 s[18:19], 0x1390080
	s_waitcnt vmcnt(0) lgkmcnt(0)
	s_barrier
	v_readlane_b32 s53, v254, 49
	v_readlane_b32 s54, v254, 50
	v_readlane_b32 s55, v254, 51
	v_readlane_b32 s58, v254, 54
	v_readlane_b32 s59, v254, 55
	v_lshlrev_b32_e32 v86, 1, v69
	v_add_u32_e32 v160, v3, v86
	v_add_u32_e32 v162, v68, v86
	v_lshlrev_b32_e32 v86, 1, v1
	v_add_u32_e32 v161, v3, v86
	v_add_u32_e32 v163, v68, v86
	v_lshrrev_b32_e32 v87, 3, v168
	v_xor_b32_e32 v86, v87, v168
	v_and_b32_e32 v86, 7, v86
	v_lshlrev_b32_e32 v86, 4, v86
	s_movk_i32 s35, 0x800
	v_mad_u32_u24 v164, v87, s35, v86
	v_add_u32_e32 v165, 0x10000, v164
	v_add_u32_e32 v166, 0x20000, v164
	v_add_u32_e32 v167, 0x30000, v164
	s_add_u32 s52, s40, 0x1390080
	s_addc_u32 s53, s41, 0
	s_add_u32 s54, s42, 0x1190080
	s_addc_u32 s55, s43, 0
	v_readfirstlane_b32 s35, v168
	s_lshl_b32 s35, s35, 4
	s_or_b32 s35, s35, 0x8000
	s_mov_b32 m0, s35
	s_nop 0
	global_load_lds_dwordx4 v164, s[52:53]
	s_add_u32 m0, s35, 0x1000
	s_nop 0
	global_load_lds_dwordx4 v165, s[52:53]
	s_add_u32 m0, s35, 0x2000
	s_nop 0
	global_load_lds_dwordx4 v166, s[52:53]
	s_add_u32 m0, s35, 0x3000
	s_nop 0
	global_load_lds_dwordx4 v167, s[52:53]
	s_add_u32 m0, s35, 0x4000
	s_nop 0
	global_load_lds_dwordx4 v164, s[54:55]
	s_add_u32 m0, s35, 0x5000
	s_nop 0
	global_load_lds_dwordx4 v165, s[54:55]
	s_add_u32 m0, s35, 0x6000
	s_nop 0
	global_load_lds_dwordx4 v166, s[54:55]
	s_add_u32 m0, s35, 0x7000
	s_nop 0
	global_load_lds_dwordx4 v167, s[54:55]
	s_add_u32 s52, s52, 0x80
	s_addc_u32 s53, s53, 0
	s_add_u32 s54, s54, 0x80
	s_addc_u32 s55, s55, 0
	s_xor_b32 s35, s35, 0x8000
	ds_read_b128 v[70:73], v160
	ds_read_b128 v[74:77], v160 offset:2048
	ds_read_b128 v[78:81], v160 offset:4096
	ds_read_b128 v[82:85], v160 offset:6144
	ds_read_b128 v[112:115], v162 offset:16384
	ds_read_b128 v[116:119], v162 offset:18432
	ds_read_b128 v[120:123], v162 offset:20480
	ds_read_b128 v[124:127], v162 offset:22528
	v_xor_b32_e32 v160, 0x8000, v160
	v_xor_b32_e32 v162, 0x8000, v162
.LBB0_149:
	ds_read_b128 v[128:131], v161
	ds_read_b128 v[132:135], v161 offset:2048
	ds_read_b128 v[136:139], v161 offset:4096
	ds_read_b128 v[140:143], v161 offset:6144
	ds_read_b128 v[144:147], v163 offset:16384
	ds_read_b128 v[148:151], v163 offset:18432
	ds_read_b128 v[152:155], v163 offset:20480
	s_waitcnt lgkmcnt(10)
	v_mfma_f32_16x16x32_bf16 v[64:67], v[112:115], v[70:73], v[64:67]
	v_mfma_f32_16x16x32_bf16 v[60:63], v[112:115], v[74:77], v[60:63]
	v_mfma_f32_16x16x32_bf16 v[56:59], v[112:115], v[78:81], v[56:59]
	v_mfma_f32_16x16x32_bf16 v[52:55], v[112:115], v[82:85], v[52:55]
	ds_read_b128 v[156:159], v163 offset:22528
	v_xor_b32_e32 v161, 0x8000, v161
	v_xor_b32_e32 v163, 0x8000, v163
	s_waitcnt lgkmcnt(10)
	v_mfma_f32_16x16x32_bf16 v[44:47], v[116:119], v[70:73], v[44:47]
	v_mfma_f32_16x16x32_bf16 v[40:43], v[116:119], v[74:77], v[40:43]
	v_mfma_f32_16x16x32_bf16 v[36:39], v[116:119], v[78:81], v[36:39]
	v_mfma_f32_16x16x32_bf16 v[28:31], v[116:119], v[82:85], v[28:31]
	s_waitcnt lgkmcnt(9)
	v_mfma_f32_16x16x32_bf16 v[24:27], v[120:123], v[70:73], v[24:27]
	v_mfma_f32_16x16x32_bf16 v[20:23], v[120:123], v[74:77], v[20:23]
	v_mfma_f32_16x16x32_bf16 v[16:19], v[120:123], v[78:81], v[16:19]
	v_mfma_f32_16x16x32_bf16 v[12:15], v[120:123], v[82:85], v[12:15]
	s_waitcnt lgkmcnt(8)
	v_mfma_f32_16x16x32_bf16 v[8:11], v[124:127], v[70:73], v[8:11]
	v_mfma_f32_16x16x32_bf16 v[4:7], v[124:127], v[74:77], v[4:7]
	v_mfma_f32_16x16x32_bf16 v[48:51], v[124:127], v[78:81], v[48:51]
	v_mfma_f32_16x16x32_bf16 v[32:35], v[124:127], v[82:85], v[32:35]
	s_waitcnt lgkmcnt(0)
	s_barrier
	s_cmp_eq_u32 s44, 0x700
	s_cbranch_scc1 .Lv4_nodma_G5
	s_mov_b32 m0, s35
	v_mfma_f32_16x16x32_bf16 v[64:67], v[144:147], v[128:131], v[64:67]
	global_load_lds_dwordx4 v164, s[52:53]
	s_add_u32 m0, s35, 0x1000
	v_mfma_f32_16x16x32_bf16 v[60:63], v[144:147], v[132:135], v[60:63]
	global_load_lds_dwordx4 v165, s[52:53]
	s_add_u32 m0, s35, 0x2000
	v_mfma_f32_16x16x32_bf16 v[56:59], v[144:147], v[136:139], v[56:59]
	global_load_lds_dwordx4 v166, s[52:53]
	s_add_u32 m0, s35, 0x3000
	v_mfma_f32_16x16x32_bf16 v[52:55], v[144:147], v[140:143], v[52:55]
	global_load_lds_dwordx4 v167, s[52:53]
	s_add_u32 m0, s35, 0x4000
	v_mfma_f32_16x16x32_bf16 v[44:47], v[148:151], v[128:131], v[44:47]
	global_load_lds_dwordx4 v164, s[54:55]
	s_add_u32 m0, s35, 0x5000
	v_mfma_f32_16x16x32_bf16 v[40:43], v[148:151], v[132:135], v[40:43]
	global_load_lds_dwordx4 v165, s[54:55]
	s_add_u32 m0, s35, 0x6000
	v_mfma_f32_16x16x32_bf16 v[36:39], v[148:151], v[136:139], v[36:39]
	global_load_lds_dwordx4 v166, s[54:55]
	s_add_u32 m0, s35, 0x7000
	v_mfma_f32_16x16x32_bf16 v[28:31], v[148:151], v[140:143], v[28:31]
	global_load_lds_dwordx4 v167, s[54:55]
	s_add_u32 s52, s52, 0x80
	s_addc_u32 s53, s53, 0
	s_add_u32 s54, s54, 0x80
	s_addc_u32 s55, s55, 0
	s_xor_b32 s35, s35, 0x8000
	s_waitcnt vmcnt(8)
	s_branch .Lv4_join_G5

.Lv4_join_G5:
	s_barrier
	ds_read_b128 v[70:73], v160
	ds_read_b128 v[74:77], v160 offset:2048
	ds_read_b128 v[78:81], v160 offset:4096
	ds_read_b128 v[82:85], v160 offset:6144
	ds_read_b128 v[112:115], v162 offset:16384
	ds_read_b128 v[116:119], v162 offset:18432
	ds_read_b128 v[120:123], v162 offset:20480
	ds_read_b128 v[124:127], v162 offset:22528
	v_xor_b32_e32 v160, 0x8000, v160
	v_xor_b32_e32 v162, 0x8000, v162
	s_add_u32 s44, s44, 0x80
	s_cmpk_eq_i32 s44, 0x780
	v_mfma_f32_16x16x32_bf16 v[24:27], v[152:155], v[128:131], v[24:27]
	v_mfma_f32_16x16x32_bf16 v[20:23], v[152:155], v[132:135], v[20:23]
	v_mfma_f32_16x16x32_bf16 v[16:19], v[152:155], v[136:139], v[16:19]
	v_mfma_f32_16x16x32_bf16 v[12:15], v[152:155], v[140:143], v[12:15]
	v_mfma_f32_16x16x32_bf16 v[8:11], v[156:159], v[128:131], v[8:11]
	v_mfma_f32_16x16x32_bf16 v[4:7], v[156:159], v[132:135], v[4:7]
	v_mfma_f32_16x16x32_bf16 v[48:51], v[156:159], v[136:139], v[48:51]
	v_mfma_f32_16x16x32_bf16 v[32:35], v[156:159], v[140:143], v[32:35]
	s_cbranch_scc0 .LBB0_149
	s_mov_b32 s39, 0x8000
	v_lshl_add_u32 v69, v69, 1, s39
	v_add_u32_e32 v90, v69, v68
	ds_read_b128 v[70:73], v90 offset:16384
	v_add_u32_e32 v69, v69, v3
	ds_read_b128 v[74:77], v69
	ds_read_b128 v[78:81], v69 offset:2048
	ds_read_b128 v[82:85], v69 offset:4096
	ds_read_b128 v[86:89], v69 offset:6144
	v_lshl_add_u32 v1, v1, 1, s39
	v_add_u32_e32 v98, v1, v68
	ds_read_b128 v[94:97], v98 offset:20480
	s_waitcnt lgkmcnt(4)
	v_mfma_f32_16x16x32_bf16 v[64:67], v[70:73], v[74:77], v[64:67]
	v_add_u32_e32 v1, v1, v3
	s_add_i32 s46, s46, 1
	v_readlane_b32 s1, v254, 22
	s_waitcnt lgkmcnt(3)
	v_mfma_f32_16x16x32_bf16 v[60:63], v[70:73], v[78:81], v[60:63]
	s_mul_i32 s2, s46, s1
	v_readlane_b32 s1, v253, 34
	s_add_i32 s2, s2, s1
	s_waitcnt lgkmcnt(2)
	v_mfma_f32_16x16x32_bf16 v[56:59], v[70:73], v[82:85], v[56:59]
	s_cmpk_gt_u32 s2, 0x5f
	s_cselect_b64 s[40:41], -1, 0
	s_lshr_b32 s44, s2, 3
	s_waitcnt lgkmcnt(1)
	v_mfma_f32_16x16x32_bf16 v[52:55], v[70:73], v[86:89], v[52:55]
	ds_read_b128 v[70:73], v90 offset:18432
	v_readlane_b32 s1, v253, 62
	s_min_u32 s3, s2, 0x60
	s_waitcnt lgkmcnt(0)
	v_mfma_f32_16x16x32_bf16 v[44:47], v[70:73], v[74:77], v[44:47]
	s_add_i32 s44, s44, s1
	s_and_b32 s45, s3, 7
	s_cmpk_lt_u32 s2, 0x60
	v_mfma_f32_16x16x32_bf16 v[40:43], v[70:73], v[78:81], v[40:43]
	v_mfma_f32_16x16x32_bf16 v[36:39], v[70:73], v[82:85], v[36:39]
	v_mfma_f32_16x16x32_bf16 v[28:31], v[70:73], v[86:89], v[28:31]
	ds_read_b128 v[70:73], v90 offset:20480
	s_waitcnt lgkmcnt(0)
	v_mfma_f32_16x16x32_bf16 v[24:27], v[70:73], v[74:77], v[24:27]
	v_mfma_f32_16x16x32_bf16 v[20:23], v[70:73], v[78:81], v[20:23]
	v_mfma_f32_16x16x32_bf16 v[16:19], v[70:73], v[82:85], v[16:19]
	v_mfma_f32_16x16x32_bf16 v[12:15], v[70:73], v[86:89], v[12:15]
	ds_read_b128 v[70:73], v90 offset:22528
	ds_read_b128 v[90:93], v1 offset:6144
	s_waitcnt lgkmcnt(1)
	v_mfma_f32_16x16x32_bf16 v[8:11], v[70:73], v[74:77], v[8:11]
	v_mfma_f32_16x16x32_bf16 v[4:7], v[70:73], v[78:81], v[4:7]
	ds_read_b128 v[78:81], v1
	v_mfma_f32_16x16x32_bf16 v[74:77], v[70:73], v[82:85], v[48:51]
	ds_read_b128 v[82:85], v1 offset:2048
	s_nop 1
	ds_read_b128 v[48:51], v98 offset:16384
	v_mfma_f32_16x16x32_bf16 v[68:71], v[70:73], v[86:89], v[32:35]
	ds_read_b128 v[86:89], v1 offset:4096
	s_nop 1
	ds_read_b128 v[32:35], v98 offset:18432
	ds_read_b128 v[98:101], v98 offset:22528
	s_waitcnt lgkmcnt(3)
	v_mfma_f32_16x16x32_bf16 v[64:67], v[48:51], v[78:81], v[64:67]
	s_waitcnt vmcnt(0)
	s_waitcnt lgkmcnt(0)
	s_barrier
	v_mfma_f32_16x16x32_bf16 v[60:63], v[48:51], v[82:85], v[60:63]
	v_mfma_f32_16x16x32_bf16 v[56:59], v[48:51], v[86:89], v[56:59]
	v_mfma_f32_16x16x32_bf16 v[52:55], v[48:51], v[90:93], v[52:55]
	v_mfma_f32_16x16x32_bf16 v[48:51], v[32:35], v[78:81], v[44:47]
	v_mfma_f32_16x16x32_bf16 v[44:47], v[32:35], v[82:85], v[40:43]
	v_mfma_f32_16x16x32_bf16 v[40:43], v[32:35], v[86:89], v[36:39]
	v_mfma_f32_16x16x32_bf16 v[36:39], v[32:35], v[90:93], v[28:31]
	v_mfma_f32_16x16x32_bf16 v[32:35], v[94:97], v[78:81], v[24:27]
	v_mfma_f32_16x16x32_bf16 v[28:31], v[94:97], v[82:85], v[20:23]
	v_mfma_f32_16x16x32_bf16 v[24:27], v[94:97], v[86:89], v[16:19]
	v_mfma_f32_16x16x32_bf16 v[20:23], v[94:97], v[90:93], v[12:15]
	v_mfma_f32_16x16x32_bf16 v[16:19], v[98:101], v[78:81], v[8:11]
	v_mfma_f32_16x16x32_bf16 v[12:15], v[98:101], v[82:85], v[4:7]
	v_mfma_f32_16x16x32_bf16 v[8:11], v[98:101], v[86:89], v[74:77]
	v_mfma_f32_16x16x32_bf16 v[4:7], v[98:101], v[90:93], v[68:71]
	s_cbranch_scc0 .LBB0_143
	v_mov_b32_e32 v1, v168
	s_lshl_b32 s2, s44, 18
	v_readlane_b32 s18, v252, 26
	v_readlane_b32 s19, v252, 27
	v_ashrrev_i32_e32 v68, 3, v1
	s_add_u32 s2, s18, s2
	v_xor_b32_e32 v3, v68, v1
	v_ashrrev_i32_e32 v69, 31, v68
	s_addc_u32 s3, s19, 0
	v_lshlrev_b64 v[68:69], 11, v[68:69]
	v_lshlrev_b32_e32 v3, 4, v3
	v_lshlrev_b32_e32 v1, 4, v1
	v_lshl_add_u64 v[70:71], s[2:3], 0, v[68:69]
	v_and_b32_e32 v72, 0x70, v3
	v_mov_b32_e32 v73, v2
	v_readfirstlane_b32 s2, v1
	v_add_u32_e32 v3, 0x1000, v1
	s_lshl_b32 s20, s45, 18
	v_readlane_b32 s1, v252, 7
	v_lshl_add_u64 v[70:71], v[70:71], 0, v[72:73]
	s_mov_b32 m0, s2
	v_readfirstlane_b32 s2, v3
	v_add_u32_e32 v3, 0x2000, v1
	s_add_u32 s20, s1, s20
	v_readlane_b32 s1, v252, 8
	global_load_lds_dwordx4 v[70:71], off
	v_lshl_add_u64 v[74:75], v[70:71], 0, s[24:25]
	s_mov_b32 m0, s2
	v_readfirstlane_b32 s2, v3
	v_add_u32_e32 v3, 0x3000, v1
	s_addc_u32 s21, s1, 0
	global_load_lds_dwordx4 v[74:75], off
	v_lshl_add_u64 v[74:75], v[70:71], 0, s[26:27]
	s_mov_b32 m0, s2
	v_readfirstlane_b32 s2, v3
	v_add_u32_e32 v3, 0x4000, v1
	v_lshl_add_u64 v[68:69], s[20:21], 0, v[68:69]
	global_load_lds_dwordx4 v[74:75], off
	v_lshl_add_u64 v[70:71], v[70:71], 0, s[28:29]
	s_mov_b32 m0, s2
	v_readfirstlane_b32 s2, v3
	v_add_u32_e32 v3, 0x5000, v1
	global_load_lds_dwordx4 v[70:71], off
	v_lshl_add_u64 v[68:69], v[68:69], 0, v[72:73]
	s_mov_b32 m0, s2
	v_readfirstlane_b32 s2, v3
	v_add_u32_e32 v3, 0x6000, v1
	global_load_lds_dwordx4 v[68:69], off
	v_lshl_add_u64 v[70:71], v[68:69], 0, s[24:25]
	s_mov_b32 m0, s2
	v_readfirstlane_b32 s2, v3
	v_add_u32_e32 v1, 0x7000, v1
	global_load_lds_dwordx4 v[70:71], off
	v_lshl_add_u64 v[70:71], v[68:69], 0, s[26:27]
	s_mov_b32 m0, s2
	v_readfirstlane_b32 s2, v1
	global_load_lds_dwordx4 v[70:71], off
	v_lshl_add_u64 v[68:69], v[68:69], 0, s[28:29]
	s_mov_b32 m0, s2
	s_nop 0
	global_load_lds_dwordx4 v[68:69], off
	s_branch .LBB0_143

.LBB0_626:
	v_mov_b32_e32 v1, v168
	v_readlane_b32 s56, v254, 48
	v_readfirstlane_b32 s2, v1
	s_lshl_b32 s3, s2, 5
	s_lshl_b32 s2, s2, 6
	s_and_b32 s3, s3, 0xfffff000
	s_and_b32 s2, s2, 0x1000
	v_readlane_b32 s60, v254, 52
	v_lshrrev_b32_e32 v3, 4, v1
	v_and_b32_e32 v4, 7, v1
	v_lshlrev_b32_e32 v1, 6, v1
	v_readlane_b32 s61, v254, 53
	s_add_u32 s48, s60, s48
	v_bitop3_b32 v3, v3, v4, 3 bitop3:0x6c
	s_waitcnt vmcnt(0)
	v_and_b32_e32 v1, 0x3c0, v1
	s_addc_u32 s49, s61, s49
	v_lshlrev_b32_e32 v69, 3, v3
	v_or_b32_e32 v3, s3, v1
	v_or_b32_e32 v4, s2, v1
	s_add_u32 s50, s60, s50
	s_waitcnt lgkmcnt(0)
	v_mov_b32_e32 v32, 0
	v_xor_b32_e32 v1, 32, v69
	s_addc_u32 s51, s61, s51
	s_mov_b64 s[52:53], 0
	s_mov_b32 s41, 0
	v_lshlrev_b32_e32 v3, 1, v3
	v_lshlrev_b32_e32 v68, 1, v4
	v_mov_b32_e32 v33, v32
	v_mov_b32_e32 v34, v32
	v_mov_b32_e32 v35, v32
	v_mov_b32_e32 v48, v32
	v_mov_b32_e32 v49, v32
	v_mov_b32_e32 v50, v32
	v_mov_b32_e32 v51, v32
	v_mov_b32_e32 v4, v32
	v_mov_b32_e32 v5, v32
	v_mov_b32_e32 v6, v32
	v_mov_b32_e32 v7, v32
	v_mov_b32_e32 v8, v32
	v_mov_b32_e32 v9, v32
	v_mov_b32_e32 v10, v32
	v_mov_b32_e32 v11, v32
	v_mov_b32_e32 v12, v32
	v_mov_b32_e32 v13, v32
	v_mov_b32_e32 v14, v32
	v_mov_b32_e32 v15, v32
	v_mov_b32_e32 v16, v32
	v_mov_b32_e32 v17, v32
	v_mov_b32_e32 v18, v32
	v_mov_b32_e32 v19, v32
	v_mov_b32_e32 v20, v32
	v_mov_b32_e32 v21, v32
	v_mov_b32_e32 v22, v32
	v_mov_b32_e32 v23, v32
	v_mov_b32_e32 v24, v32
	v_mov_b32_e32 v25, v32
	v_mov_b32_e32 v26, v32
	v_mov_b32_e32 v27, v32
	v_mov_b32_e32 v28, v32
	v_mov_b32_e32 v29, v32
	v_mov_b32_e32 v30, v32
	v_mov_b32_e32 v31, v32
	v_mov_b32_e32 v36, v32
	v_mov_b32_e32 v37, v32
	v_mov_b32_e32 v38, v32
	v_mov_b32_e32 v39, v32
	v_mov_b32_e32 v40, v32
	v_mov_b32_e32 v41, v32
	v_mov_b32_e32 v42, v32
	v_mov_b32_e32 v43, v32
	v_mov_b32_e32 v44, v32
	v_mov_b32_e32 v45, v32
	v_mov_b32_e32 v46, v32
	v_mov_b32_e32 v47, v32
	v_mov_b32_e32 v52, v32
	v_mov_b32_e32 v53, v32
	v_mov_b32_e32 v54, v32
	v_mov_b32_e32 v55, v32
	v_mov_b32_e32 v56, v32
	v_mov_b32_e32 v57, v32
	v_mov_b32_e32 v58, v32
	v_mov_b32_e32 v59, v32
	v_mov_b32_e32 v60, v32
	v_mov_b32_e32 v61, v32
	v_mov_b32_e32 v62, v32
	v_mov_b32_e32 v63, v32
	v_mov_b32_e32 v64, v32
	v_mov_b32_e32 v65, v32
	v_mov_b32_e32 v66, v32
	v_mov_b32_e32 v67, v32
	s_waitcnt vmcnt(0)
	s_barrier
	v_readlane_b32 s57, v254, 49
	v_readlane_b32 s58, v254, 50
	v_readlane_b32 s59, v254, 51
	v_readlane_b32 s62, v254, 54
	v_readlane_b32 s63, v254, 55
	v_lshlrev_b32_e32 v86, 1, v69
	v_add_u32_e32 v160, v3, v86
	v_add_u32_e32 v162, v68, v86
	v_lshlrev_b32_e32 v86, 1, v1
	v_add_u32_e32 v161, v3, v86
	v_add_u32_e32 v163, v68, v86
	v_lshrrev_b32_e32 v87, 3, v168
	v_xor_b32_e32 v86, v87, v168
	v_and_b32_e32 v86, 7, v86
	v_lshlrev_b32_e32 v86, 4, v86
	s_movk_i32 s60, 0x800
	v_mad_u32_u24 v164, v87, s60, v86
	v_add_u32_e32 v165, 0x10000, v164
	v_add_u32_e32 v166, 0x20000, v164
	v_add_u32_e32 v167, 0x30000, v164
	s_add_u32 s56, s48, s68
	s_addc_u32 s57, s49, s69
	s_add_u32 s58, s50, 0x80080
	s_addc_u32 s59, s51, 0
	v_readfirstlane_b32 s60, v168
	s_lshl_b32 s60, s60, 4
	s_or_b32 s60, s60, 0x8000
	s_mov_b32 m0, s60
	s_nop 0
	global_load_lds_dwordx4 v164, s[56:57]
	s_add_u32 m0, s60, 0x1000
	s_nop 0
	global_load_lds_dwordx4 v165, s[56:57]
	s_add_u32 m0, s60, 0x2000
	s_nop 0
	global_load_lds_dwordx4 v166, s[56:57]
	s_add_u32 m0, s60, 0x3000
	s_nop 0
	global_load_lds_dwordx4 v167, s[56:57]
	s_add_u32 m0, s60, 0x4000
	s_nop 0
	global_load_lds_dwordx4 v164, s[58:59]
	s_add_u32 m0, s60, 0x5000
	s_nop 0
	global_load_lds_dwordx4 v165, s[58:59]
	s_add_u32 m0, s60, 0x6000
	s_nop 0
	global_load_lds_dwordx4 v166, s[58:59]
	s_add_u32 m0, s60, 0x7000
	s_nop 0
	global_load_lds_dwordx4 v167, s[58:59]
	s_add_u32 s56, s56, 0x80
	s_addc_u32 s57, s57, 0
	s_add_u32 s58, s58, 0x80
	s_addc_u32 s59, s59, 0
	s_xor_b32 s60, s60, 0x8000
	ds_read_b128 v[70:73], v160
	ds_read_b128 v[74:77], v160 offset:2048
	ds_read_b128 v[78:81], v160 offset:4096
	ds_read_b128 v[82:85], v160 offset:6144
	ds_read_b128 v[112:115], v162 offset:16384
	ds_read_b128 v[116:119], v162 offset:18432
	ds_read_b128 v[120:123], v162 offset:20480
	ds_read_b128 v[124:127], v162 offset:22528
	v_xor_b32_e32 v160, 0x8000, v160
	v_xor_b32_e32 v162, 0x8000, v162
.LBB0_627:
	ds_read_b128 v[128:131], v161
	ds_read_b128 v[132:135], v161 offset:2048
	ds_read_b128 v[136:139], v161 offset:4096
	ds_read_b128 v[140:143], v161 offset:6144
	ds_read_b128 v[144:147], v163 offset:16384
	ds_read_b128 v[148:151], v163 offset:18432
	ds_read_b128 v[152:155], v163 offset:20480
	s_waitcnt lgkmcnt(10)
	v_mfma_f32_16x16x32_bf16 v[64:67], v[112:115], v[70:73], v[64:67]
	v_mfma_f32_16x16x32_bf16 v[60:63], v[112:115], v[74:77], v[60:63]
	v_mfma_f32_16x16x32_bf16 v[56:59], v[112:115], v[78:81], v[56:59]
	v_mfma_f32_16x16x32_bf16 v[52:55], v[112:115], v[82:85], v[52:55]
	ds_read_b128 v[156:159], v163 offset:22528
	v_xor_b32_e32 v161, 0x8000, v161
	v_xor_b32_e32 v163, 0x8000, v163
	s_waitcnt lgkmcnt(10)
	v_mfma_f32_16x16x32_bf16 v[44:47], v[116:119], v[70:73], v[44:47]
	v_mfma_f32_16x16x32_bf16 v[40:43], v[116:119], v[74:77], v[40:43]
	v_mfma_f32_16x16x32_bf16 v[36:39], v[116:119], v[78:81], v[36:39]
	v_mfma_f32_16x16x32_bf16 v[28:31], v[116:119], v[82:85], v[28:31]
	s_waitcnt lgkmcnt(9)
	v_mfma_f32_16x16x32_bf16 v[24:27], v[120:123], v[70:73], v[24:27]
	v_mfma_f32_16x16x32_bf16 v[20:23], v[120:123], v[74:77], v[20:23]
	v_mfma_f32_16x16x32_bf16 v[16:19], v[120:123], v[78:81], v[16:19]
	v_mfma_f32_16x16x32_bf16 v[12:15], v[120:123], v[82:85], v[12:15]
	s_waitcnt lgkmcnt(8)
	v_mfma_f32_16x16x32_bf16 v[8:11], v[124:127], v[70:73], v[8:11]
	v_mfma_f32_16x16x32_bf16 v[4:7], v[124:127], v[74:77], v[4:7]
	v_mfma_f32_16x16x32_bf16 v[48:51], v[124:127], v[78:81], v[48:51]
	v_mfma_f32_16x16x32_bf16 v[32:35], v[124:127], v[82:85], v[32:35]
	s_waitcnt lgkmcnt(0)
	s_barrier
	s_cmp_eq_u32 s52, 0x700
	s_cbranch_scc1 .Lv4_nodma_G1
	s_mov_b32 m0, s60
	v_mfma_f32_16x16x32_bf16 v[64:67], v[144:147], v[128:131], v[64:67]
	global_load_lds_dwordx4 v164, s[56:57]
	s_add_u32 m0, s60, 0x1000
	v_mfma_f32_16x16x32_bf16 v[60:63], v[144:147], v[132:135], v[60:63]
	global_load_lds_dwordx4 v165, s[56:57]
	s_add_u32 m0, s60, 0x2000
	v_mfma_f32_16x16x32_bf16 v[56:59], v[144:147], v[136:139], v[56:59]
	global_load_lds_dwordx4 v166, s[56:57]
	s_add_u32 m0, s60, 0x3000
	v_mfma_f32_16x16x32_bf16 v[52:55], v[144:147], v[140:143], v[52:55]
	global_load_lds_dwordx4 v167, s[56:57]
	s_add_u32 m0, s60, 0x4000
	v_mfma_f32_16x16x32_bf16 v[44:47], v[148:151], v[128:131], v[44:47]
	global_load_lds_dwordx4 v164, s[58:59]
	s_add_u32 m0, s60, 0x5000
	v_mfma_f32_16x16x32_bf16 v[40:43], v[148:151], v[132:135], v[40:43]
	global_load_lds_dwordx4 v165, s[58:59]
	s_add_u32 m0, s60, 0x6000
	v_mfma_f32_16x16x32_bf16 v[36:39], v[148:151], v[136:139], v[36:39]
	global_load_lds_dwordx4 v166, s[58:59]
	s_add_u32 m0, s60, 0x7000
	v_mfma_f32_16x16x32_bf16 v[28:31], v[148:151], v[140:143], v[28:31]
	global_load_lds_dwordx4 v167, s[58:59]
	s_add_u32 s56, s56, 0x80
	s_addc_u32 s57, s57, 0
	s_add_u32 s58, s58, 0x80
	s_addc_u32 s59, s59, 0
	s_xor_b32 s60, s60, 0x8000
	s_waitcnt vmcnt(8)
	s_branch .Lv4_join_G1

.Lv4_join_G1:
	s_barrier
	ds_read_b128 v[70:73], v160
	ds_read_b128 v[74:77], v160 offset:2048
	ds_read_b128 v[78:81], v160 offset:4096
	ds_read_b128 v[82:85], v160 offset:6144
	ds_read_b128 v[112:115], v162 offset:16384
	ds_read_b128 v[116:119], v162 offset:18432
	ds_read_b128 v[120:123], v162 offset:20480
	ds_read_b128 v[124:127], v162 offset:22528
	v_xor_b32_e32 v160, 0x8000, v160
	v_xor_b32_e32 v162, 0x8000, v162
	s_add_u32 s52, s52, 0x80
	s_cmpk_eq_i32 s52, 0x780
	v_mfma_f32_16x16x32_bf16 v[24:27], v[152:155], v[128:131], v[24:27]
	v_mfma_f32_16x16x32_bf16 v[20:23], v[152:155], v[132:135], v[20:23]
	v_mfma_f32_16x16x32_bf16 v[16:19], v[152:155], v[136:139], v[16:19]
	v_mfma_f32_16x16x32_bf16 v[12:15], v[152:155], v[140:143], v[12:15]
	v_mfma_f32_16x16x32_bf16 v[8:11], v[156:159], v[128:131], v[8:11]
	v_mfma_f32_16x16x32_bf16 v[4:7], v[156:159], v[132:135], v[4:7]
	v_mfma_f32_16x16x32_bf16 v[48:51], v[156:159], v[136:139], v[48:51]
	v_mfma_f32_16x16x32_bf16 v[32:35], v[156:159], v[140:143], v[32:35]
	s_cbranch_scc0 .LBB0_627
	s_mov_b32 s37, 0x8000
	v_lshl_add_u32 v69, v69, 1, s37
	v_add_u32_e32 v90, v69, v68
	ds_read_b128 v[70:73], v90 offset:16384
	v_add_u32_e32 v69, v69, v3
	ds_read_b128 v[74:77], v69
	ds_read_b128 v[78:81], v69 offset:2048
	ds_read_b128 v[82:85], v69 offset:4096
	ds_read_b128 v[86:89], v69 offset:6144
	v_lshl_add_u32 v1, v1, 1, s37
	v_add_u32_e32 v98, v1, v68
	ds_read_b128 v[94:97], v98 offset:20480
	s_waitcnt lgkmcnt(4)
	v_mfma_f32_16x16x32_bf16 v[64:67], v[70:73], v[74:77], v[64:67]
	v_add_u32_e32 v1, v1, v3
	s_and_b64 vcc, exec, s[46:47]
	s_waitcnt lgkmcnt(3)
	v_mfma_f32_16x16x32_bf16 v[60:63], v[70:73], v[78:81], v[60:63]
	s_waitcnt lgkmcnt(2)
	v_mfma_f32_16x16x32_bf16 v[56:59], v[70:73], v[82:85], v[56:59]
	s_waitcnt lgkmcnt(1)
	v_mfma_f32_16x16x32_bf16 v[52:55], v[70:73], v[86:89], v[52:55]
	ds_read_b128 v[70:73], v90 offset:18432
	s_waitcnt lgkmcnt(0)
	v_mfma_f32_16x16x32_bf16 v[44:47], v[70:73], v[74:77], v[44:47]
	v_mfma_f32_16x16x32_bf16 v[40:43], v[70:73], v[78:81], v[40:43]
	v_mfma_f32_16x16x32_bf16 v[36:39], v[70:73], v[82:85], v[36:39]
	v_mfma_f32_16x16x32_bf16 v[28:31], v[70:73], v[86:89], v[28:31]
	ds_read_b128 v[70:73], v90 offset:20480
	s_waitcnt lgkmcnt(0)
	v_mfma_f32_16x16x32_bf16 v[24:27], v[70:73], v[74:77], v[24:27]
	v_mfma_f32_16x16x32_bf16 v[20:23], v[70:73], v[78:81], v[20:23]
	v_mfma_f32_16x16x32_bf16 v[16:19], v[70:73], v[82:85], v[16:19]
	v_mfma_f32_16x16x32_bf16 v[12:15], v[70:73], v[86:89], v[12:15]
	ds_read_b128 v[70:73], v90 offset:22528
	ds_read_b128 v[90:93], v1 offset:6144
	s_waitcnt lgkmcnt(1)
	v_mfma_f32_16x16x32_bf16 v[8:11], v[70:73], v[74:77], v[8:11]
	v_mfma_f32_16x16x32_bf16 v[4:7], v[70:73], v[78:81], v[4:7]
	ds_read_b128 v[78:81], v1
	v_mfma_f32_16x16x32_bf16 v[74:77], v[70:73], v[82:85], v[48:51]
	ds_read_b128 v[82:85], v1 offset:2048
	s_nop 1
	ds_read_b128 v[48:51], v98 offset:16384
	v_mfma_f32_16x16x32_bf16 v[68:71], v[70:73], v[86:89], v[32:35]
	ds_read_b128 v[86:89], v1 offset:4096
	s_nop 1
	ds_read_b128 v[32:35], v98 offset:18432
	s_waitcnt lgkmcnt(2)
	v_mfma_f32_16x16x32_bf16 v[64:67], v[48:51], v[78:81], v[64:67]
	v_mfma_f32_16x16x32_bf16 v[60:63], v[48:51], v[82:85], v[60:63]
	s_waitcnt lgkmcnt(1)
	v_mfma_f32_16x16x32_bf16 v[56:59], v[48:51], v[86:89], v[56:59]
	v_mfma_f32_16x16x32_bf16 v[52:55], v[48:51], v[90:93], v[52:55]
	s_waitcnt lgkmcnt(0)
	v_mfma_f32_16x16x32_bf16 v[48:51], v[32:35], v[78:81], v[44:47]
	v_mfma_f32_16x16x32_bf16 v[44:47], v[32:35], v[82:85], v[40:43]
	v_mfma_f32_16x16x32_bf16 v[40:43], v[32:35], v[86:89], v[36:39]
	v_mfma_f32_16x16x32_bf16 v[36:39], v[32:35], v[90:93], v[28:31]
	v_mfma_f32_16x16x32_bf16 v[32:35], v[94:97], v[78:81], v[24:27]
	v_mfma_f32_16x16x32_bf16 v[28:31], v[94:97], v[82:85], v[20:23]
	v_mfma_f32_16x16x32_bf16 v[24:27], v[94:97], v[86:89], v[16:19]
	v_mfma_f32_16x16x32_bf16 v[20:23], v[94:97], v[90:93], v[12:15]
	ds_read_b128 v[94:97], v98 offset:22528
	s_waitcnt vmcnt(0)
	s_waitcnt lgkmcnt(0)
	v_mfma_f32_16x16x32_bf16 v[16:19], v[94:97], v[78:81], v[8:11]
	s_barrier
	v_mfma_f32_16x16x32_bf16 v[12:15], v[94:97], v[82:85], v[4:7]
	v_mfma_f32_16x16x32_bf16 v[8:11], v[94:97], v[86:89], v[74:77]
	v_mfma_f32_16x16x32_bf16 v[4:7], v[94:97], v[90:93], v[68:71]
	s_cbranch_vccz .LBB0_630
	s_ashr_i32 s41, s40, 31
	v_mov_b32_e32 v1, v168
	s_lshl_b64 s[20:21], s[40:41], 18
	v_readlane_b32 s2, v252, 32
	v_readlane_b32 s3, v252, 33
	v_ashrrev_i32_e32 v68, 3, v1
	s_add_u32 s20, s2, s20
	v_xor_b32_e32 v3, v68, v1
	v_ashrrev_i32_e32 v69, 31, v68
	s_addc_u32 s21, s3, s21
	v_lshlrev_b64 v[68:69], 11, v[68:69]
	v_lshlrev_b32_e32 v3, 4, v3
	v_lshlrev_b32_e32 v1, 4, v1
	s_ashr_i32 s43, s42, 31
	v_lshl_add_u64 v[70:71], s[20:21], 0, v[68:69]
	v_and_b32_e32 v72, 0x70, v3
	v_mov_b32_e32 v73, v2
	v_readfirstlane_b32 s2, v1
	v_add_u32_e32 v3, 0x1000, v1
	s_lshl_b64 s[46:47], s[42:43], 18
	v_readlane_b32 s1, v252, 19
	v_lshl_add_u64 v[70:71], v[70:71], 0, v[72:73]
	s_mov_b32 m0, s2
	v_readfirstlane_b32 s2, v3
	v_add_u32_e32 v3, 0x2000, v1
	s_add_u32 s46, s1, s46
	v_readlane_b32 s1, v252, 20
	global_load_lds_dwordx4 v[70:71], off
	v_lshl_add_u64 v[74:75], v[70:71], 0, s[24:25]
	s_mov_b32 m0, s2
	v_readfirstlane_b32 s2, v3
	v_add_u32_e32 v3, 0x3000, v1
	s_addc_u32 s47, s1, s47
	global_load_lds_dwordx4 v[74:75], off
	v_lshl_add_u64 v[74:75], v[70:71], 0, s[26:27]
	s_mov_b32 m0, s2
	v_readfirstlane_b32 s2, v3
	v_add_u32_e32 v3, 0x4000, v1
	v_lshl_add_u64 v[68:69], s[46:47], 0, v[68:69]
	global_load_lds_dwordx4 v[74:75], off
	v_lshl_add_u64 v[70:71], v[70:71], 0, s[28:29]
	s_mov_b32 m0, s2
	v_readfirstlane_b32 s2, v3
	v_add_u32_e32 v3, 0x5000, v1
	global_load_lds_dwordx4 v[70:71], off
	v_lshl_add_u64 v[68:69], v[68:69], 0, v[72:73]
	s_mov_b32 m0, s2
	v_readfirstlane_b32 s2, v3
	v_add_u32_e32 v3, 0x6000, v1
	global_load_lds_dwordx4 v[68:69], off
	v_lshl_add_u64 v[70:71], v[68:69], 0, s[24:25]
	s_mov_b32 m0, s2
	v_readfirstlane_b32 s2, v3
	v_add_u32_e32 v1, 0x7000, v1
	global_load_lds_dwordx4 v[70:71], off
	v_lshl_add_u64 v[70:71], v[68:69], 0, s[26:27]
	s_mov_b32 m0, s2
	v_readfirstlane_b32 s2, v1
	global_load_lds_dwordx4 v[70:71], off
	v_lshl_add_u64 v[68:69], v[68:69], 0, s[28:29]
	s_mov_b32 m0, s2
	s_nop 0
	global_load_lds_dwordx4 v[68:69], off
